# v3 + layer-1 w_out/w_gate transposes before the phase-6 barrier by atomic ticket (2 tiles each), next ticket fetched early
# speedup vs baseline: 1.0053x; 1.0053x over previous
; #define LAS __attribute__((address_space(3)))
; template <bool REMAP = false>
; __device__ __forceinline__ void transpose_convert(LAS unsigned char* lds, const float* src, bf16_t* dst, int K, int N, int G, int bid) {
;     LAS float* tile = (LAS float*)lds;
;     const int tid = threadIdx.x, ntn = N / 64, ntiles = (K / 128) * ntn;
;     const int r0 = tid >> 4, c4 = tid & 15;
;     f32x4 v[4];
;     if (bid < ntiles) { const int k0 = (bid / ntn) * 128, n0 = (bid % ntn) * 64;
; #pragma unroll
;         for (int i = 0; i < 4; ++i) v[i] = __builtin_nontemporal_load((const f32x4*)(src + (size_t)(k0 + r0 + 32 * i) * N + n0 + c4 * 4)); }
;     for (int t = bid; t < ntiles; t += G) {
;         const int k0 = (t / ntn) * 128, n0 = (t % ntn) * 64;
; __global__ void __launch_bounds__(NTHREADS, 2) mk_fwd(Params P) {
;     ...
;         transpose_convert(lds, P.w_out + (size_t)2048 * 2048, WOUT1, 2048, 2048, G, bid);
;         transpose_convert(lds, P.w_gate + (size_t)2048 * 2048, WG1, 2048, 2048, G, bid);
.LBB0_570:
	s_waitcnt vmcnt(0)
	s_barrier
	s_mov_b64 s[100:101], s[16:17]
	s_add_u32 s24, s40, 0x2000000
	s_addc_u32 s25, s41, 0
	s_add_u32 s22, s40, 0x2800000
	s_addc_u32 s23, s41, 0
	s_movk_i32 s98, 0x100
	v_mov_b32_e32 v46, 0x20008
	s_add_u32 s10, s54, 0xa000
	s_addc_u32 s11, s55, 0
	s_and_saveexec_b64 s[18:19], s[12:13]
	s_cbranch_execz .Ldyn7_nofirst
	v_mov_b32_e32 v0, 0
	v_mov_b32_e32 v47, 1
	global_atomic_add v47, v0, v47, s[10:11] sc0
	s_waitcnt vmcnt(0)

; #define LAS __attribute__((address_space(3)))
; template <bool REMAP = false>
; __device__ __forceinline__ void transpose_convert(LAS unsigned char* lds, const float* src, bf16_t* dst, int K, int N, int G, int bid) {
;     LAS float* tile = (LAS float*)lds;
;     const int tid = threadIdx.x, ntn = N / 64, ntiles = (K / 128) * ntn;
;     const int r0 = tid >> 4, c4 = tid & 15;
;     f32x4 v[4];
;     if (bid < ntiles) { const int k0 = (bid / ntn) * 128, n0 = (bid % ntn) * 64;
; #pragma unroll
;         for (int i = 0; i < 4; ++i) v[i] = __builtin_nontemporal_load((const f32x4*)(src + (size_t)(k0 + r0 + 32 * i) * N + n0 + c4 * 4)); }
;     for (int t = bid; t < ntiles; t += G) {
;         const int k0 = (t / ntn) * 128, n0 = (t % ntn) * 64;
.Ldyn7_top:
	s_waitcnt lgkmcnt(0)
	s_barrier
	s_add_u32 s10, s54, 0xa000
	s_addc_u32 s11, s55, 0
	s_and_saveexec_b64 s[18:19], s[12:13]
	s_cbranch_execz .Ldyn7_nofetch
	s_waitcnt vmcnt(4)
	ds_write_b32 v46, v47
	v_mov_b32_e32 v0, 0
	v_mov_b32_e32 v1, 1
	s_waitcnt lgkmcnt(0)
	global_atomic_add v47, v0, v1, s[10:11] sc0
.Ldyn7_nofetch:
	s_or_b64 exec, exec, s[18:19]
	s_waitcnt lgkmcnt(0)
	s_barrier
	ds_read_b32 v1, v46
	s_waitcnt lgkmcnt(0)
	v_readfirstlane_b32 s99, v1
	s_nop 3
	s_cmp_gt_u32 s99, 0x1ff
	s_cbranch_scc1 .Ldyn7_exit
	s_cmpk_lt_i32 s99, 0x200
	s_cselect_b64 s[4:5], -1, 0
	s_cmpk_gt_i32 s99, 0xff
	v_lshl_add_u32 v20, v214, 2, 0
	s_cbranch_scc1 .Ldyn7_call2pre
	s_add_u32 s6, s44, 0x1000000
	s_addc_u32 s7, s45, 0
	s_ashr_i32 s8, s99, 31
	s_lshr_b32 s8, s8, 27
	s_add_i32 s8, s99, s8
	s_lshl_b32 s9, s8, 2
	s_and_b32 s8, s8, 0x3ffffe0
	s_sub_i32 s8, s99, s8
	s_and_b32 s9, s9, 0xffffff80
	s_lshl_b32 s8, s8, 6
	s_waitcnt vmcnt(0)
	v_or_b32_e32 v8, s9, v214
	s_ashr_i32 s9, s8, 31
	s_lshl_b64 s[8:9], s[8:9], 2
	v_and_b32_e32 v24, 15, v164
	s_add_u32 s8, s6, s8
	s_addc_u32 s9, s7, s9
	v_lshlrev_b32_e32 v18, 4, v24
	v_mov_b32_e32 v19, 0
	v_ashrrev_i32_e32 v9, 31, v8
	v_lshl_add_u64 v[10:11], s[8:9], 0, v[18:19]
	v_lshlrev_b64 v[0:1], 13, v[8:9]
	v_lshl_add_u64 v[12:13], v[10:11], 0, v[0:1]
	s_mov_b32 s10, 0x40000
	v_or_b32_e32 v8, 64, v8
	v_add_co_u32_e32 v14, vcc, s10, v12
	v_ashrrev_i32_e32 v9, 31, v8
	s_nop 0
	v_addc_co_u32_e32 v15, vcc, 0, v13, vcc
	v_lshlrev_b64 v[8:9], 13, v[8:9]
	s_mov_b32 s11, 0xc0000
	v_lshl_add_u64 v[16:17], v[10:11], 0, v[8:9]
	v_add_co_u32_e32 v22, vcc, s11, v12
	global_load_dwordx4 v[0:3], v[12:13], off nt
	global_load_dwordx4 v[4:7], v[14:15], off nt
	v_addc_co_u32_e32 v23, vcc, 0, v13, vcc
	global_load_dwordx4 v[8:11], v[16:17], off nt
	global_load_dwordx4 v[12:15], v[22:23], off nt
	v_add_u32_e32 v21, 0x200, v164
	v_add_u32_e32 v22, 0, v18
	v_lshrrev_b32_e32 v21, 4, v21
	v_mul_u32_u24_e32 v23, 0x104, v214
	v_lshl_add_u32 v27, v21, 2, 0
	v_mul_u32_u24_e32 v28, 0x820, v24
	v_add_u32_e32 v22, v22, v23
	v_lshl_add_u64 v[16:17], s[6:7], 0, v[18:19]
	v_lshl_add_u64 v[18:19], s[24:25], 0, v[18:19]
	s_lshl_b32 s17, s99, 6
	s_lshl_b32 s16, s98, 6
	v_add_u32_e32 v23, 0x2080, v22
	v_add_u32_e32 v24, 0x2088, v22
	v_add_u32_e32 v25, 0x4100, v22
	v_add_u32_e32 v26, v20, v28
	v_add_u32_e32 v27, v27, v28
	v_add_u32_e32 v28, 0x4108, v22
	v_add_u32_e32 v29, 0x6180, v22
	s_mov_b32 s18, s99
	s_branch .LBB0_625

; #define LAS __attribute__((address_space(3)))
; template <bool REMAP = false>
; __device__ __forceinline__ void transpose_convert(LAS unsigned char* lds, const float* src, bf16_t* dst, int K, int N, int G, int bid) {
;     LAS float* tile = (LAS float*)lds;
;     const int tid = threadIdx.x, ntn = N / 64, ntiles = (K / 128) * ntn;
;     const int r0 = tid >> 4, c4 = tid & 15;
;     f32x4 v[4];
;     if (bid < ntiles) { const int k0 = (bid / ntn) * 128, n0 = (bid % ntn) * 64;
; #pragma unroll
;         for (int i = 0; i < 4; ++i) v[i] = __builtin_nontemporal_load((const f32x4*)(src + (size_t)(k0 + r0 + 32 * i) * N + n0 + c4 * 4)); }
;     ...
;         if (t + G < ntiles) { const int k1 = ((t + G) / ntn) * 128, n1 = ((t + G) % ntn) * 64;
; #pragma unroll
;             for (int i = 0; i < 4; ++i) v[i] = __builtin_nontemporal_load((const f32x4*)(src + (size_t)(k1 + r0 + 32 * i) * N + n1 + c4 * 4)); }
.LBB0_627:
	s_andn2_b64 vcc, exec, s[8:9]
	s_cbranch_vccnz .LBB0_624
	s_ashr_i32 s8, s19, 31
	s_lshr_b32 s8, s8, 27
	s_add_i32 s8, s19, s8
	s_ashr_i32 s9, s8, 5
	s_add_i32 s28, s16, s17
	s_lshl_b32 s8, s9, 11
	s_sub_i32 s8, s28, s8
	v_lshl_or_b32 v8, s9, 7, v214
	s_ashr_i32 s9, s8, 31
	v_ashrrev_i32_e32 v9, 31, v8
	v_lshl_add_u64 v[10:11], s[8:9], 2, v[16:17]
	v_lshlrev_b64 v[0:1], 13, v[8:9]
	v_lshl_add_u64 v[12:13], v[10:11], 0, v[0:1]
	v_add_co_u32_e32 v14, vcc, s10, v12
	v_or_b32_e32 v8, 64, v8
	s_nop 0
	v_addc_co_u32_e32 v15, vcc, 0, v13, vcc
	v_ashrrev_i32_e32 v9, 31, v8
	global_load_dwordx4 v[0:3], v[12:13], off nt
	global_load_dwordx4 v[4:7], v[14:15], off nt
	v_lshlrev_b64 v[8:9], 13, v[8:9]
	v_add_co_u32_e32 v12, vcc, s11, v12
	v_lshl_add_u64 v[8:9], v[10:11], 0, v[8:9]
	s_nop 0
	v_addc_co_u32_e32 v13, vcc, 0, v13, vcc
	global_load_dwordx4 v[8:11], v[8:9], off nt
	s_nop 0
	global_load_dwordx4 v[12:15], v[12:13], off nt
	s_branch .LBB0_624
.LBB0_629:
	s_branch .Ldyn7_top
.Ldyn7_call2pre:
	s_sub_u32 s99, s99, 0x100
	s_add_u32 s4, s50, 0x1000000
	s_addc_u32 s5, s51, 0
	s_ashr_i32 s6, s99, 31
	s_lshr_b32 s6, s6, 27
	s_add_i32 s6, s99, s6
	s_lshl_b32 s7, s6, 2
	s_and_b32 s6, s6, 0x3ffffe0
	s_sub_i32 s6, s99, s6
	s_and_b32 s7, s7, 0xffffff80
	s_lshl_b32 s6, s6, 6
	v_or_b32_e32 v8, s7, v214
	s_ashr_i32 s7, s6, 31
	s_lshl_b64 s[6:7], s[6:7], 2
	v_and_b32_e32 v24, 15, v164
	s_add_u32 s6, s4, s6
	s_addc_u32 s7, s5, s7
	v_lshlrev_b32_e32 v18, 4, v24
	v_mov_b32_e32 v19, 0
	v_ashrrev_i32_e32 v9, 31, v8
	v_lshl_add_u64 v[10:11], s[6:7], 0, v[18:19]
	v_lshlrev_b64 v[0:1], 13, v[8:9]
	v_lshl_add_u64 v[12:13], v[10:11], 0, v[0:1]
	s_mov_b32 s8, 0x40000
	v_or_b32_e32 v8, 64, v8
	v_add_co_u32_e32 v14, vcc, s8, v12
	v_ashrrev_i32_e32 v9, 31, v8
	s_nop 0
	v_addc_co_u32_e32 v15, vcc, 0, v13, vcc
	v_lshlrev_b64 v[8:9], 13, v[8:9]
	s_mov_b32 s9, 0xc0000
	v_lshl_add_u64 v[16:17], v[10:11], 0, v[8:9]
	v_add_co_u32_e32 v22, vcc, s9, v12
	global_load_dwordx4 v[0:3], v[12:13], off nt
	global_load_dwordx4 v[4:7], v[14:15], off nt
	v_addc_co_u32_e32 v23, vcc, 0, v13, vcc
	global_load_dwordx4 v[8:11], v[16:17], off nt
	global_load_dwordx4 v[12:15], v[22:23], off nt
	v_add_u32_e32 v21, 0x200, v164
	v_add_u32_e32 v22, 0, v18
	v_lshrrev_b32_e32 v21, 4, v21
	v_mul_u32_u24_e32 v23, 0x104, v214
	v_lshl_add_u32 v26, v21, 2, 0
	v_mul_u32_u24_e32 v27, 0x820, v24
	v_add_u32_e32 v22, v22, v23
	v_lshl_add_u64 v[16:17], s[4:5], 0, v[18:19]
	v_lshl_add_u64 v[18:19], s[22:23], 0, v[18:19]
	s_lshl_b32 s11, s99, 6
	s_lshl_b32 s10, s98, 6
	v_add_u32_e32 v23, 0x2080, v22
	v_add_u32_e32 v24, 0x2088, v22
	v_add_u32_e32 v25, 0x4100, v22
	v_add_u32_e32 v20, v20, v27
	v_add_u32_e32 v26, v26, v27
	v_add_u32_e32 v27, 0x4108, v22
	v_add_u32_e32 v28, 0x6180, v22
	s_mov_b32 s16, s99
	s_branch .LBB0_632
